# E51: E44 plus attention tile loop back edge rotated (v_mov hoisted above a single s_cbranch_scc0; strategy 9 loop-edge edit)
# speedup vs baseline: 1.0029x; 1.0009x over previous
.LBB0_2199:
	v_cndmask_b32_e64 v188, v133, v188, s[6:7]
	v_mul_f32_e32 v112, 0xbdd53b94, v188
	v_mov_b32_e32 v113, v112
	v_fmamk_f32 v80, v80, 0x3dd53b94, v112
	v_fmamk_f32 v81, v81, 0x3dd53b94, v112
	v_fmamk_f32 v82, v82, 0x3dd53b94, v112
	v_fmamk_f32 v83, v83, 0x3dd53b94, v112
	v_fmamk_f32 v84, v84, 0x3dd53b94, v112
	v_fmamk_f32 v85, v85, 0x3dd53b94, v112
	v_fmamk_f32 v86, v86, 0x3dd53b94, v112
	v_fmamk_f32 v87, v87, 0x3dd53b94, v112
	v_fmamk_f32 v88, v88, 0x3dd53b94, v112
	v_fmamk_f32 v89, v89, 0x3dd53b94, v112
	v_fmamk_f32 v90, v90, 0x3dd53b94, v112
	v_fmamk_f32 v91, v91, 0x3dd53b94, v112
	v_fmamk_f32 v92, v92, 0x3dd53b94, v112
	v_fmamk_f32 v93, v93, 0x3dd53b94, v112
	v_fmamk_f32 v94, v94, 0x3dd53b94, v112
	v_fmac_f32_e32 v113, 0x3dd53b94, v95
	v_exp_f32_e32 v133, v80
	v_exp_f32_e32 v214, v81
	v_exp_f32_e32 v134, v82
	v_exp_f32_e32 v215, v83
	v_exp_f32_e32 v213, v84
	v_exp_f32_e32 v216, v85
	v_exp_f32_e32 v135, v86
	v_exp_f32_e32 v212, v87
	v_exp_f32_e32 v146, v88
	v_exp_f32_e32 v148, v89
	v_exp_f32_e32 v147, v90
	v_exp_f32_e32 v149, v91
	v_exp_f32_e32 v128, v92
	v_exp_f32_e32 v130, v93
	v_exp_f32_e32 v129, v94
	v_exp_f32_e32 v131, v113
	v_pk_fma_f32 v[126:127], v[64:65], s[72:73], v[112:113] op_sel_hi:[1,0,0]
	v_add_f32_e32 v64, v209, v210
	s_mov_b64 s[6:7], 0xc000
	v_fmac_f32_e32 v64, v189, v151
	v_add_f32_e32 v151, v217, v218
	v_lshl_add_u64 v[142:143], v[142:143], 0, s[6:7]
	s_add_i32 s85, s85, 2
	s_mov_b64 s[6:7], 0x8000
	v_pk_fma_f32 v[124:125], v[66:67], s[72:73], v[112:113] op_sel_hi:[1,0,0]
	v_pk_fma_f32 v[120:121], v[68:69], s[72:73], v[112:113] op_sel_hi:[1,0,0]
	v_pk_fma_f32 v[116:117], v[70:71], s[72:73], v[112:113] op_sel_hi:[1,0,0]
	v_pk_fma_f32 v[114:115], v[72:73], s[72:73], v[112:113] op_sel_hi:[1,0,0]
	v_pk_fma_f32 v[122:123], v[74:75], s[72:73], v[112:113] op_sel_hi:[1,0,0]
	v_pk_fma_f32 v[118:119], v[76:77], s[72:73], v[112:113] op_sel_hi:[1,0,0]
	v_pk_fma_f32 v[112:113], v[78:79], s[72:73], v[112:113] op_sel_hi:[1,0,0]
	v_fmac_f32_e32 v151, v64, v211
	s_cmp_ge_u32 s85, s84
	v_lshl_add_u64 v[144:145], v[144:145], 0, s[6:7]
	s_waitcnt lgkmcnt(0)
	s_barrier
	v_mov_b32_e32 v189, v132
	s_cbranch_scc0 .LBB0_2191
